# IN prompt tiles on the merged-phase 256x256 core with routed epilogue (f32 16-B + paired 16-B bf16 stores); sample-row tiles stay on the original code
# speedup vs baseline: 1.0125x; 1.0066x over previous
; #define BAR() { __builtin_amdgcn_sched_barrier(0); __builtin_amdgcn_s_barrier(); asm volatile("" ::: "memory"); __builtin_amdgcn_sched_barrier(0); }
; DI void gemm_stream2(const bf16_t* __restrict__ A, int lda, const bf16_t* __restrict__ Bt, int ldb, int K, int m0, int n0, ...
;     ...
;     const int wave = __builtin_amdgcn_readfirstlane(tid >> 6), lane = tid & 63, wm = wave >> 1, wn = wave & 1, r = lane & 15, q = lane >> 4;
;     const int sc0 = ((lane & 7) ^ (lane >> 4)) * 8, sc1 = ((lane & 7) ^ (4 | (lane >> 4))) * 8;
;     const bf16_t* ga = A + (size_t)(m0 + wave * 32 + (lane >> 3)) * lda;
;     const bf16_t* gb = Bt + (size_t)(n0 + wave * 16 + (lane >> 3)) * ldb;
;     const bf16_t* gan = An + (size_t)(m0n + wave * 32 + (lane >> 3)) * ldan;
;     const bf16_t* gbn = Btn + (size_t)(n0n + wave * 16 + (lane >> 3)) * ldbn;
;     const unsigned wa = (unsigned)wave * 4096u, wbb = 32768u + (unsigned)wave * 2048u;
;     ...
;     const int sw = r >> 1;
;     const unsigned fo0 = (unsigned)(r * 128 + ((q ^ sw) << 4)), fo1 = (unsigned)(r * 128 + (((q ^ sw) ^ 4) << 4));
;     const unsigned aoff = (unsigned)(wm * 64) * 128u, boff = 32768u + (unsigned)(wn * 64) * 128u;
;     const int nk = K / 64;
;     const int grp = wave >> 2;
;     ...
;     int st = rg.st;
;     if (!rg.primed) {
;         const int s1p = st == 2 ? 0 : st + 1;
;         BAR();
;         STAGE(st, 0);
;         STAGE(s1p, 1);
;         asm volatile("s_waitcnt vmcnt(6)" ::: "memory");
;         BAR();
;     }
;     if (grp == 1) BAR();
; DI void gemm_in(const Params& p, int l, int bid, int nb, char* smem, const int tid) {
;     const bf16_t* A = (const bf16_t*)(p.ws + B_XN);
;     const bf16_t* Bt = (const bf16_t*)(p.ws + W_IN);
;     const int ntn = 16, ntiles = 130 * ntn;
;     const int lane = tid & 63, wave = __builtin_amdgcn_readfirstlane(tid >> 6), wm = wave >> 1, wn = wave & 1, r = lane & 15, q = lane >> 4;
;     TileIter ti; ti.init(65, ntn, bid, nb);
;     int tm, tn, tm2 = 0, tn2 = 0;
;     bool have = ti.next(tm, tn);
;     Ring rg; rg.st = 0; rg.primed = 0;
;     for (; have; tm = tm2, tn = tn2) {
;         have = ti.next(tm2, tn2);
;         const int m0 = tm * 256, n0 = tn * 128;
;         f32x4 acc[4][4]; zero_acc(acc);
;         gemm_stream(A, 1024, Bt, 1024, 1024, m0, n0, have, tm2 * 256, tn2 * 128, smem, acc, tid, rg);
.Lin_ranged:
	s_cmp_ge_u32 s51, s52
	s_cbranch_scc1 .Lin_stub
	v_and_b32_e32 v190, 63, v193
	v_and_b32_e32 v191, 15, v190
	v_lshrrev_b32_e32 v17, 4, v190
	v_lshrrev_b32_e32 v18, 3, v190
	v_and_b32_e32 v19, 7, v190
	v_xor_b32_e32 v195, v19, v17
	v_lshlrev_b32_e32 v195, 4, v195
	v_lshl_add_u32 v184, v18, 11, v195
	v_or_b32_e32 v195, 4, v17
	v_xor_b32_e32 v195, v19, v195
	v_lshlrev_b32_e32 v195, 4, v195
	v_add_u32_e32 v227, 8, v18
	v_lshl_add_u32 v185, v227, 11, v195
	v_lshrrev_b32_e32 v195, 1, v191
	v_xor_b32_e32 v195, v17, v195
	v_lshlrev_b32_e32 v195, 4, v195
	s_lshl_b32 s1, s33, 6
	v_add_u32_e32 v230, s1, v191
	v_lshl_add_u32 v186, v230, 7, v195
	v_xor_b32_e32 v187, 64, v186
	s_lshl_b32 s1, s36, 5
	v_add_u32_e32 v227, s1, v191
	v_lshl_add_u32 v188, v227, 7, v195
	v_add_u32_e32 v188, 0x10000, v188
	v_xor_b32_e32 v189, 64, v188
	s_lshl_b32 s1, s36, 7
	v_lshl_add_u32 v236, v17, 4, s1
	v_lshrrev_b32_e32 v228, 1, v236
	v_lshl_add_u32 v237, v230, 9, v228
	v_and_b32_e32 v227, 1, v17
	v_mul_u32_u24_e32 v227, 0x1ff8, v227
	v_add_u32_e32 v229, v237, v227
	s_lshr_b32 s1, s51, 6
	s_and_b32 s2, s51, 63
	s_lshr_b32 s58, s2, 3
	s_and_b32 s2, s2, 7
	s_lshl_b32 s1, s1, 3
	s_add_i32 s57, s1, s2
	s_lshl_b32 s1, s57, 19
	s_lshl_b32 s2, s10, 15
	s_add_u32 s1, s1, s2
	s_add_u32 s1, s1, 0x3240000
	s_add_u32 s66, s88, s1
	s_addc_u32 s67, s89, 0
	s_add_u32 s68, s66, 0x40000
	s_addc_u32 s69, s67, 0
	s_lshl_b32 s1, s58, 19
	s_add_u32 s1, s1, s2
	s_add_u32 s1, s1, s61
	s_add_u32 s70, s88, s1
	s_addc_u32 s71, s89, 0
	s_add_u32 s72, s70, 0x40000
	s_addc_u32 s73, s71, 0
	s_add_i32 m0, s39, 0x10000
	s_nop 0
	global_load_lds_dwordx4 v184, s[70:71]
	s_add_i32 m0, s39, 0x10400
	s_nop 0
	global_load_lds_dwordx4 v185, s[70:71]
	s_add_u32 s70, s70, 0x80
	s_addc_u32 s71, s71, 0
	s_add_i32 m0, s39, 0x0
	s_nop 0
	global_load_lds_dwordx4 v184, s[66:67]
	s_add_i32 m0, s39, 0x400
	s_nop 0
	global_load_lds_dwordx4 v185, s[66:67]
	s_add_u32 s66, s66, 0x80
	s_addc_u32 s67, s67, 0
	s_add_i32 m0, s39, 0x14000
	s_nop 0
	global_load_lds_dwordx4 v184, s[72:73]
	s_add_i32 m0, s39, 0x14400
	s_nop 0
	global_load_lds_dwordx4 v185, s[72:73]
	s_add_u32 s72, s72, 0x80
	s_addc_u32 s73, s73, 0
	s_add_i32 m0, s39, 0x4000
	s_nop 0
	global_load_lds_dwordx4 v184, s[68:69]
	s_add_i32 m0, s39, 0x4400
	s_nop 0
	global_load_lds_dwordx4 v185, s[68:69]
	s_add_u32 s68, s68, 0x80
	s_addc_u32 s69, s69, 0
	s_add_i32 m0, s39, 0x18000
	s_nop 0
	global_load_lds_dwordx4 v184, s[70:71]
	s_add_i32 m0, s39, 0x18400
	s_nop 0
	global_load_lds_dwordx4 v185, s[70:71]
	s_add_u32 s70, s70, 0x80
	s_addc_u32 s71, s71, 0
	s_add_i32 m0, s39, 0x8000
	s_nop 0
	global_load_lds_dwordx4 v184, s[66:67]
	s_add_i32 m0, s39, 0x8400
	s_nop 0
	global_load_lds_dwordx4 v185, s[66:67]
	s_add_u32 s66, s66, 0x80
	s_addc_u32 s67, s67, 0
	s_add_i32 m0, s39, 0x1c000
	s_nop 0
	global_load_lds_dwordx4 v184, s[72:73]
	s_add_i32 m0, s39, 0x1c400
	s_nop 0
	global_load_lds_dwordx4 v185, s[72:73]
	s_add_u32 s72, s72, 0x80
	s_addc_u32 s73, s73, 0
	s_waitcnt vmcnt(8)
	s_barrier
	s_cmp_eq_u32 s33, 0
	s_cbranch_scc1 .Lin_lead
	s_barrier
.Lin_lead:
.Lin_tile:
	s_add_u32 s76, s51, s53
	s_cmp_lt_u32 s76, s52
	s_cselect_b32 s54, 1, 0
	s_cbranch_scc0 .Lin_nonext
	s_lshr_b32 s1, s76, 6
	s_and_b32 s2, s76, 63
	s_lshr_b32 s60, s2, 3
	s_and_b32 s2, s2, 7
	s_lshl_b32 s1, s1, 3
	s_add_i32 s59, s1, s2
	s_lshl_b32 s1, s59, 19
	s_lshl_b32 s2, s10, 15
	s_add_u32 s1, s1, s2
	s_add_u32 s1, s1, 0x3240000
	s_add_u32 s74, s88, s1
	s_addc_u32 s75, s89, 0
	s_add_u32 s78, s74, 0x40000
	s_addc_u32 s79, s75, 0
	s_lshl_b32 s1, s60, 19
	s_add_u32 s1, s1, s2
	s_add_u32 s1, s1, s61
	s_add_u32 s80, s88, s1
	s_addc_u32 s81, s89, 0
	s_add_u32 s82, s80, 0x40000
	s_addc_u32 s83, s81, 0

; DI unsigned pk2(float lo, float hi) { const f32x2 v = {lo, hi}; return __builtin_bit_cast(unsigned, __builtin_convertvector(v, bf2_t)); }
; DI void gemm_in(const Params& p, int l, int bid, int nb, char* smem, const int tid) {
;     ...
;             const size_t boff = seg == 1 ? B_KA : seg == 2 ? B_VA : seg == 4 ? B_KC : B_VC;
;             const bool samp = m0 >= NP;
;             const size_t ooff = samp ? (seg == 1 ? O_AKS : seg == 2 ? O_AVS : seg == 4 ? O_CKS : O_CVS) : (seg == 1 ? O_AKP : seg == 2 ? O_AVP : seg == 4 ? O_CKP : O_CVP);
;             bf16_t* KV = (bf16_t*)(p.ws + boff);
; #pragma unroll
;             for (int mi = 0; mi < 4; ++mi) {
;                 const int row = m0 + wm * 64 + mi * 16 + r;
;                 const size_t srow = samp ? (size_t)(l * NS + (row - NP)) : (size_t)(l * NP + row);
;                 const size_t kr = (size_t)krow_of(row);
; #pragma unroll
;                 for (int ni = 0; ni < 4; ++ni) {
;                     const int c = cin + ni * 16 + q * 4;
;                     *(f32x4*)(p.out + ooff + srow * 256 + c) = acc[mi][ni];
;                     u32x2 w; w.x = pk2(acc[mi][ni][0], acc[mi][ni][1]); w.y = pk2(acc[mi][ni][2], acc[mi][ni][3]);
;                     *(u32x2*)(KV + kr * 256 + c) = w;
;                 }
;             }
.Lin_epi:
	s_nop 7
	s_nop 7
	s_cmp_eq_u32 s58, 0
	s_cbranch_scc1 .Lin_q1
	s_cmp_eq_u32 s58, 3
	s_cbranch_scc1 .Lin_q1
	s_cmp_ge_u32 s58, 6
	s_cbranch_scc1 .Lin_sm1
	s_mov_b32 s1, 0xb500000
	s_mov_b32 s62, 0x9fc0000
	s_cmp_eq_u32 s58, 4
	s_cselect_b32 s1, 0x9500000, s1
	s_cselect_b32 s62, 0x93a0000, s62
	s_cmp_eq_u32 s58, 2
	s_cselect_b32 s1, 0x6100000, s1
	s_cselect_b32 s62, 0x8780000, s62
	s_cmp_eq_u32 s58, 1
	s_cselect_b32 s1, 0x4100000, s1
	s_cselect_b32 s62, 0x7b60000, s62
	v_readlane_b32 s37, v231, 4
	s_lshl_b32 s37, s37, 24
	s_add_u32 s1, s1, s37
	s_lshl_b32 s37, s57, 18
	s_add_u32 s1, s1, s37
	v_readlane_b32 s2, v240, 5
	v_readlane_b32 s3, v240, 6
	s_nop 3
	s_add_u32 s2, s2, s1
	s_addc_u32 s3, s3, 0
	s_lshl_b32 s37, s57, 17
	s_add_u32 s62, s62, s37
	s_add_u32 s96, s88, s62
	s_addc_u32 s97, s89, 0
	v_lshlrev_b32_e32 v172, 1, v237
	global_store_dwordx4 v172, v[24:27], s[2:3] offset:0
	global_store_dwordx4 v172, v[28:31], s[2:3] offset:64
	global_store_dwordx4 v172, v[56:59], s[2:3] offset:512
	global_store_dwordx4 v172, v[60:63], s[2:3] offset:576
	s_add_u32 s2, s2, 0x4000
	s_addc_u32 s3, s3, 0
	global_store_dwordx4 v172, v[32:35], s[2:3] offset:0
	global_store_dwordx4 v172, v[36:39], s[2:3] offset:64
	global_store_dwordx4 v172, v[64:67], s[2:3] offset:512
	global_store_dwordx4 v172, v[68:71], s[2:3] offset:576
	s_add_u32 s2, s2, 0x4000
	s_addc_u32 s3, s3, 0
	v_cvt_pk_bf16_f32 v152, v24, v25
	v_cvt_pk_bf16_f32 v153, v26, v27
	v_cvt_pk_bf16_f32 v154, v32, v33
	v_cvt_pk_bf16_f32 v155, v34, v35
	s_nop 1
	v_permlane16_swap_b32_e32 v152, v154
	v_permlane16_swap_b32_e32 v153, v155
	global_store_dwordx4 v229, v[152:155], s[96:97] offset:0
	v_cvt_pk_bf16_f32 v156, v28, v29
	v_cvt_pk_bf16_f32 v157, v30, v31
	v_cvt_pk_bf16_f32 v158, v36, v37
	v_cvt_pk_bf16_f32 v159, v38, v39
	s_nop 1
	v_permlane16_swap_b32_e32 v156, v158
	v_permlane16_swap_b32_e32 v157, v159
	global_store_dwordx4 v229, v[156:159], s[96:97] offset:32
	v_cvt_pk_bf16_f32 v160, v56, v57
	v_cvt_pk_bf16_f32 v161, v58, v59
	v_cvt_pk_bf16_f32 v162, v64, v65
	v_cvt_pk_bf16_f32 v163, v66, v67
	s_nop 1
	v_permlane16_swap_b32_e32 v160, v162
	v_permlane16_swap_b32_e32 v161, v163
	global_store_dwordx4 v229, v[160:163], s[96:97] offset:256
	v_cvt_pk_bf16_f32 v164, v60, v61
	v_cvt_pk_bf16_f32 v165, v62, v63
	v_cvt_pk_bf16_f32 v166, v68, v69
	v_cvt_pk_bf16_f32 v167, v70, v71
	s_nop 1
	v_permlane16_swap_b32_e32 v164, v166
	v_permlane16_swap_b32_e32 v165, v167
	global_store_dwordx4 v229, v[164:167], s[96:97] offset:288
	s_add_u32 s96, s96, 0x4000
	s_addc_u32 s97, s97, 0
	global_store_dwordx4 v172, v[40:43], s[2:3] offset:0
	global_store_dwordx4 v172, v[44:47], s[2:3] offset:64
	global_store_dwordx4 v172, v[72:75], s[2:3] offset:512
	global_store_dwordx4 v172, v[76:79], s[2:3] offset:576
	s_add_u32 s2, s2, 0x4000
	s_addc_u32 s3, s3, 0
	global_store_dwordx4 v172, v[48:51], s[2:3] offset:0
	global_store_dwordx4 v172, v[52:55], s[2:3] offset:64
	global_store_dwordx4 v172, v[80:83], s[2:3] offset:512
	global_store_dwordx4 v172, v[84:87], s[2:3] offset:576
	s_add_u32 s2, s2, 0x14000
	s_addc_u32 s3, s3, 0
	v_cvt_pk_bf16_f32 v152, v40, v41
	v_cvt_pk_bf16_f32 v153, v42, v43
	v_cvt_pk_bf16_f32 v154, v48, v49
	v_cvt_pk_bf16_f32 v155, v50, v51
	s_nop 1
	v_permlane16_swap_b32_e32 v152, v154
	v_permlane16_swap_b32_e32 v153, v155
	global_store_dwordx4 v229, v[152:155], s[96:97] offset:0
	v_cvt_pk_bf16_f32 v156, v44, v45
	v_cvt_pk_bf16_f32 v157, v46, v47
	v_cvt_pk_bf16_f32 v158, v52, v53
	v_cvt_pk_bf16_f32 v159, v54, v55
	s_nop 1
	v_permlane16_swap_b32_e32 v156, v158
	v_permlane16_swap_b32_e32 v157, v159
	global_store_dwordx4 v229, v[156:159], s[96:97] offset:32
	v_cvt_pk_bf16_f32 v160, v72, v73
	v_cvt_pk_bf16_f32 v161, v74, v75
	v_cvt_pk_bf16_f32 v162, v80, v81
	v_cvt_pk_bf16_f32 v163, v82, v83
	s_nop 1
	v_permlane16_swap_b32_e32 v160, v162
	v_permlane16_swap_b32_e32 v161, v163
	global_store_dwordx4 v229, v[160:163], s[96:97] offset:256
	v_cvt_pk_bf16_f32 v164, v76, v77
	v_cvt_pk_bf16_f32 v165, v78, v79
	v_cvt_pk_bf16_f32 v166, v84, v85
	v_cvt_pk_bf16_f32 v167, v86, v87
	s_nop 1
	v_permlane16_swap_b32_e32 v164, v166
	v_permlane16_swap_b32_e32 v165, v167
	global_store_dwordx4 v229, v[164:167], s[96:97] offset:288
	s_add_u32 s96, s96, 0xc000
	s_addc_u32 s97, s97, 0
	global_store_dwordx4 v172, v[88:91], s[2:3] offset:0
	global_store_dwordx4 v172, v[92:95], s[2:3] offset:64
	global_store_dwordx4 v172, v[120:123], s[2:3] offset:512
	global_store_dwordx4 v172, v[124:127], s[2:3] offset:576
	s_add_u32 s2, s2, 0x4000
	s_addc_u32 s3, s3, 0
	global_store_dwordx4 v172, v[96:99], s[2:3] offset:0
	global_store_dwordx4 v172, v[100:103], s[2:3] offset:64
	global_store_dwordx4 v172, v[128:131], s[2:3] offset:512
	global_store_dwordx4 v172, v[132:135], s[2:3] offset:576
	s_add_u32 s2, s2, 0x4000
	s_addc_u32 s3, s3, 0
	v_cvt_pk_bf16_f32 v152, v88, v89
	v_cvt_pk_bf16_f32 v153, v90, v91
	v_cvt_pk_bf16_f32 v154, v96, v97
	v_cvt_pk_bf16_f32 v155, v98, v99
	s_nop 1
	v_permlane16_swap_b32_e32 v152, v154
	v_permlane16_swap_b32_e32 v153, v155
	global_store_dwordx4 v229, v[152:155], s[96:97] offset:0
	v_cvt_pk_bf16_f32 v156, v92, v93
	v_cvt_pk_bf16_f32 v157, v94, v95
	v_cvt_pk_bf16_f32 v158, v100, v101
	v_cvt_pk_bf16_f32 v159, v102, v103
	s_nop 1
	v_permlane16_swap_b32_e32 v156, v158
	v_permlane16_swap_b32_e32 v157, v159
	global_store_dwordx4 v229, v[156:159], s[96:97] offset:32
	v_cvt_pk_bf16_f32 v160, v120, v121
	v_cvt_pk_bf16_f32 v161, v122, v123
	v_cvt_pk_bf16_f32 v162, v128, v129
	v_cvt_pk_bf16_f32 v163, v130, v131
	s_nop 1
	v_permlane16_swap_b32_e32 v160, v162
	v_permlane16_swap_b32_e32 v161, v163
; DI unsigned pk2(float lo, float hi) { const f32x2 v = {lo, hi}; return __builtin_bit_cast(unsigned, __builtin_convertvector(v, bf2_t)); }
; DI void gemm_in(const Params& p, int l, int bid, int nb, char* smem, const int tid) {
;     ...
;         if (seg == 0 || seg == 3) {
;             bf16_t* Q = (bf16_t*)(p.ws + (seg == 0 ? B_QA : B_QC));
; #pragma unroll
;             for (int mi = 0; mi < 4; ++mi) {
;                 const int row = m0 + wm * 64 + mi * 16 + r;
; #pragma unroll
;                 for (int ni = 0; ni < 4; ++ni) {
;                     u32x2 w; w.x = pk2(acc[mi][ni][0], acc[mi][ni][1]); w.y = pk2(acc[mi][ni][2], acc[mi][ni][3]);
;                     *(u32x2*)(Q + (size_t)row * 256 + cin + ni * 16 + q * 4) = w;
;                 }
;             }
;         } else if (seg < 6) {
;             const size_t boff = seg == 1 ? B_KA : seg == 2 ? B_VA : seg == 4 ? B_KC : B_VC;
;             const bool samp = m0 >= NP;
;             const size_t ooff = samp ? (seg == 1 ? O_AKS : seg == 2 ? O_AVS : seg == 4 ? O_CKS : O_CVS) : (seg == 1 ? O_AKP : seg == 2 ? O_AVP : seg == 4 ? O_CKP : O_CVP);
;             bf16_t* KV = (bf16_t*)(p.ws + boff);
; #pragma unroll
;             for (int mi = 0; mi < 4; ++mi) {
;                 const int row = m0 + wm * 64 + mi * 16 + r;
;                 const size_t srow = samp ? (size_t)(l * NS + (row - NP)) : (size_t)(l * NP + row);
;                 const size_t kr = (size_t)krow_of(row);
; #pragma unroll
;                 for (int ni = 0; ni < 4; ++ni) {
;                     const int c = cin + ni * 16 + q * 4;
;                     *(f32x4*)(p.out + ooff + srow * 256 + c) = acc[mi][ni];
;                     u32x2 w; w.x = pk2(acc[mi][ni][0], acc[mi][ni][1]); w.y = pk2(acc[mi][ni][2], acc[mi][ni][3]);
;                     *(u32x2*)(KV + kr * 256 + c) = w;
;                 }
;             }
	global_store_dwordx4 v229, v[160:163], s[96:97] offset:256
	v_cvt_pk_bf16_f32 v164, v124, v125
	v_cvt_pk_bf16_f32 v165, v126, v127
	v_cvt_pk_bf16_f32 v166, v132, v133
	v_cvt_pk_bf16_f32 v167, v134, v135
	s_nop 1
	v_permlane16_swap_b32_e32 v164, v166
	v_permlane16_swap_b32_e32 v165, v167
	global_store_dwordx4 v229, v[164:167], s[96:97] offset:288
	s_add_u32 s96, s96, 0x4000
	s_addc_u32 s97, s97, 0
	global_store_dwordx4 v172, v[104:107], s[2:3] offset:0
	global_store_dwordx4 v172, v[108:111], s[2:3] offset:64
	global_store_dwordx4 v172, v[136:139], s[2:3] offset:512
	global_store_dwordx4 v172, v[140:143], s[2:3] offset:576
	s_add_u32 s2, s2, 0x4000
	s_addc_u32 s3, s3, 0
	global_store_dwordx4 v172, v[112:115], s[2:3] offset:0
	global_store_dwordx4 v172, v[116:119], s[2:3] offset:64
	global_store_dwordx4 v172, v[144:147], s[2:3] offset:512
	global_store_dwordx4 v172, v[148:151], s[2:3] offset:576
	v_cvt_pk_bf16_f32 v152, v104, v105
	v_cvt_pk_bf16_f32 v153, v106, v107
	v_cvt_pk_bf16_f32 v154, v112, v113
	v_cvt_pk_bf16_f32 v155, v114, v115
	s_nop 1
	v_permlane16_swap_b32_e32 v152, v154
	v_permlane16_swap_b32_e32 v153, v155
	global_store_dwordx4 v229, v[152:155], s[96:97] offset:0
	v_cvt_pk_bf16_f32 v156, v108, v109
	v_cvt_pk_bf16_f32 v157, v110, v111
	v_cvt_pk_bf16_f32 v158, v116, v117
	v_cvt_pk_bf16_f32 v159, v118, v119
	s_nop 1
	v_permlane16_swap_b32_e32 v156, v158
	v_permlane16_swap_b32_e32 v157, v159
	global_store_dwordx4 v229, v[156:159], s[96:97] offset:32
	v_cvt_pk_bf16_f32 v160, v136, v137
	v_cvt_pk_bf16_f32 v161, v138, v139
	v_cvt_pk_bf16_f32 v162, v144, v145
	v_cvt_pk_bf16_f32 v163, v146, v147
	s_nop 1
	v_permlane16_swap_b32_e32 v160, v162
	v_permlane16_swap_b32_e32 v161, v163
	global_store_dwordx4 v229, v[160:163], s[96:97] offset:256
	v_cvt_pk_bf16_f32 v164, v140, v141
	v_cvt_pk_bf16_f32 v165, v142, v143
	v_cvt_pk_bf16_f32 v166, v148, v149
	v_cvt_pk_bf16_f32 v167, v150, v151
	s_nop 1
	v_permlane16_swap_b32_e32 v164, v166
	v_permlane16_swap_b32_e32 v165, v167
	global_store_dwordx4 v229, v[164:167], s[96:97] offset:288
	s_branch .Lin_done1
.Lin_q1:
	s_mov_b32 s62, 0x5ae0000
	s_cmp_eq_u32 s58, 0
	s_cselect_b32 s62, 0x52c0000, s62
	s_lshl_b32 s37, s57, 17
	s_add_u32 s62, s62, s37
	s_add_u32 s96, s88, s62
	s_addc_u32 s97, s89, 0
	v_cvt_pk_bf16_f32 v152, v24, v25
	v_cvt_pk_bf16_f32 v153, v26, v27
	v_cvt_pk_bf16_f32 v154, v32, v33
	v_cvt_pk_bf16_f32 v155, v34, v35
	s_nop 1
	v_permlane16_swap_b32_e32 v152, v154
	v_permlane16_swap_b32_e32 v153, v155
	global_store_dwordx4 v229, v[152:155], s[96:97] offset:0
	v_cvt_pk_bf16_f32 v156, v28, v29
	v_cvt_pk_bf16_f32 v157, v30, v31
	v_cvt_pk_bf16_f32 v158, v36, v37
	v_cvt_pk_bf16_f32 v159, v38, v39
	s_nop 1
	v_permlane16_swap_b32_e32 v156, v158
	v_permlane16_swap_b32_e32 v157, v159
	global_store_dwordx4 v229, v[156:159], s[96:97] offset:32
	v_cvt_pk_bf16_f32 v160, v56, v57
	v_cvt_pk_bf16_f32 v161, v58, v59
	v_cvt_pk_bf16_f32 v162, v64, v65
	v_cvt_pk_bf16_f32 v163, v66, v67
	s_nop 1
	v_permlane16_swap_b32_e32 v160, v162
	v_permlane16_swap_b32_e32 v161, v163
	global_store_dwordx4 v229, v[160:163], s[96:97] offset:256
	v_cvt_pk_bf16_f32 v164, v60, v61
	v_cvt_pk_bf16_f32 v165, v62, v63
	v_cvt_pk_bf16_f32 v166, v68, v69
	v_cvt_pk_bf16_f32 v167, v70, v71
	s_nop 1
	v_permlane16_swap_b32_e32 v164, v166
	v_permlane16_swap_b32_e32 v165, v167
	global_store_dwordx4 v229, v[164:167], s[96:97] offset:288
	s_add_u32 s96, s96, 0x4000
	s_addc_u32 s97, s97, 0
	v_cvt_pk_bf16_f32 v152, v40, v41
	v_cvt_pk_bf16_f32 v153, v42, v43
	v_cvt_pk_bf16_f32 v154, v48, v49
	v_cvt_pk_bf16_f32 v155, v50, v51
	s_nop 1
	v_permlane16_swap_b32_e32 v152, v154
	v_permlane16_swap_b32_e32 v153, v155
	global_store_dwordx4 v229, v[152:155], s[96:97] offset:0
	v_cvt_pk_bf16_f32 v156, v44, v45
	v_cvt_pk_bf16_f32 v157, v46, v47
	v_cvt_pk_bf16_f32 v158, v52, v53
	v_cvt_pk_bf16_f32 v159, v54, v55
	s_nop 1
	v_permlane16_swap_b32_e32 v156, v158
	v_permlane16_swap_b32_e32 v157, v159
	global_store_dwordx4 v229, v[156:159], s[96:97] offset:32
	v_cvt_pk_bf16_f32 v160, v72, v73
	v_cvt_pk_bf16_f32 v161, v74, v75
	v_cvt_pk_bf16_f32 v162, v80, v81
	v_cvt_pk_bf16_f32 v163, v82, v83
	s_nop 1
	v_permlane16_swap_b32_e32 v160, v162
	v_permlane16_swap_b32_e32 v161, v163
	global_store_dwordx4 v229, v[160:163], s[96:97] offset:256
	v_cvt_pk_bf16_f32 v164, v76, v77
	v_cvt_pk_bf16_f32 v165, v78, v79
	v_cvt_pk_bf16_f32 v166, v84, v85
	v_cvt_pk_bf16_f32 v167, v86, v87
	s_nop 1
	v_permlane16_swap_b32_e32 v164, v166
	v_permlane16_swap_b32_e32 v165, v167
	global_store_dwordx4 v229, v[164:167], s[96:97] offset:288
	s_add_u32 s96, s96, 0xc000
	s_addc_u32 s97, s97, 0
	v_cvt_pk_bf16_f32 v152, v88, v89
	v_cvt_pk_bf16_f32 v153, v90, v91
	v_cvt_pk_bf16_f32 v154, v96, v97
	v_cvt_pk_bf16_f32 v155, v98, v99
	s_nop 1
	v_permlane16_swap_b32_e32 v152, v154
	v_permlane16_swap_b32_e32 v153, v155
	global_store_dwordx4 v229, v[152:155], s[96:97] offset:0
	v_cvt_pk_bf16_f32 v156, v92, v93
	v_cvt_pk_bf16_f32 v157, v94, v95
	v_cvt_pk_bf16_f32 v158, v100, v101
	v_cvt_pk_bf16_f32 v159, v102, v103
	s_nop 1
	v_permlane16_swap_b32_e32 v156, v158
	v_permlane16_swap_b32_e32 v157, v159
	global_store_dwordx4 v229, v[156:159], s[96:97] offset:32
	v_cvt_pk_bf16_f32 v160, v120, v121
	v_cvt_pk_bf16_f32 v161, v122, v123
	v_cvt_pk_bf16_f32 v162, v128, v129
	v_cvt_pk_bf16_f32 v163, v130, v131
	s_nop 1
	v_permlane16_swap_b32_e32 v160, v162
	v_permlane16_swap_b32_e32 v161, v163
	global_store_dwordx4 v229, v[160:163], s[96:97] offset:256
	v_cvt_pk_bf16_f32 v164, v124, v125
	v_cvt_pk_bf16_f32 v165, v126, v127
	v_cvt_pk_bf16_f32 v166, v132, v133
	v_cvt_pk_bf16_f32 v167, v134, v135
	s_nop 1
	v_permlane16_swap_b32_e32 v164, v166
	v_permlane16_swap_b32_e32 v165, v167
	global_store_dwordx4 v229, v[164:167], s[96:97] offset:288
	s_add_u32 s96, s96, 0x4000
	s_addc_u32 s97, s97, 0
	v_cvt_pk_bf16_f32 v152, v104, v105
	v_cvt_pk_bf16_f32 v153, v106, v107
	v_cvt_pk_bf16_f32 v154, v112, v113
	v_cvt_pk_bf16_f32 v155, v114, v115
	s_nop 1
	v_permlane16_swap_b32_e32 v152, v154
	v_permlane16_swap_b32_e32 v153, v155
	global_store_dwordx4 v229, v[152:155], s[96:97] offset:0
	v_cvt_pk_bf16_f32 v156, v108, v109
	v_cvt_pk_bf16_f32 v157, v110, v111
	v_cvt_pk_bf16_f32 v158, v116, v117
	v_cvt_pk_bf16_f32 v159, v118, v119
	s_nop 1
	v_permlane16_swap_b32_e32 v156, v158
	v_permlane16_swap_b32_e32 v157, v159
	global_store_dwordx4 v229, v[156:159], s[96:97] offset:32
	v_cvt_pk_bf16_f32 v160, v136, v137
	v_cvt_pk_bf16_f32 v161, v138, v139
	v_cvt_pk_bf16_f32 v162, v144, v145
	v_cvt_pk_bf16_f32 v163, v146, v147
	s_nop 1
	v_permlane16_swap_b32_e32 v160, v162
	v_permlane16_swap_b32_e32 v161, v163
	global_store_dwordx4 v229, v[160:163], s[96:97] offset:256
	v_cvt_pk_bf16_f32 v164, v140, v141
	v_cvt_pk_bf16_f32 v165, v142, v143
	v_cvt_pk_bf16_f32 v166, v148, v149
	v_cvt_pk_bf16_f32 v167, v150, v151
	s_nop 1
	v_permlane16_swap_b32_e32 v164, v166
	v_permlane16_swap_b32_e32 v165, v167
	global_store_dwordx4 v229, v[164:167], s[96:97] offset:288
	s_branch .Lin_done1
